# hgrn local: second item's raw rows prefetched into spare registers in the middle of the first item (cross-item software pipelining)
# baseline (speedup 1.0000x reference)
; #define LAS __attribute__((address_space(3)))
; #define HG_LAUNDER() do { asm volatile("" : "+v"(lane)); l15 = lane & 15; q = lane >> 4; } while (0)
; template <bool OUT> __device__ __forceinline__ HRaw hgrn_loadc(const PA& a, int bh, int c, int chunk, int lane) {
;     const bf16* pr = (const bf16*)(a.ws + WS_PROJ) + ((size_t)(bh >> 2) * T + (size_t)c * 128 + chunk * 16 + (lane >> 3)) * DIN + (bh & 3) * 64 + (lane & 7) * 8;
;     HRaw r;
; #pragma unroll
;     for (int k = 0; k < 2; ++k) { r.f[k] = *(const v4u*)(pr + (size_t)(8 * k) * DIN + 256); r.v[k] = *(const v4u*)(pr + (size_t)(8 * k) * DIN + 512);
;         if (OUT) { r.q[k] = *(const v4u*)(pr + (size_t)(8 * k) * DIN); } }
; template <bool OUT> __device__ __forceinline__ void hgrn_chunk(const PA& a, LAS unsigned char* wb, LAS float* DLk, LAS float* E7k, LAS float* DALLk, int layer, int h, int lane, const HRaw& raw, ...
;     ...
;         const int rr = lane >> 3, cc = (lane & 7) * 8;
; #pragma unroll
;         for (int k = 0; k < 2; ++k) { *(LAS v4u*)(RF + (rr + 8 * k) * 72 + cc) = raw.f[k]; *(LAS v4u*)(RV + (rr + 8 * k) * 72 + cc) = raw.v[k]; if (OUT) *(LAS v4u*)(RQ + (rr + 8 * k) * 72 + cc) = raw.q[k]; }
; template <bool OUT> __device__ __forceinline__ void hgrn_pair(const PA& a, LAS unsigned char* lds, int layer, int bh, int s, int wave, int lane) {
;     ...
;     { const HRaw r0 = hgrn_loadc<OUT>(a, bh, c, 2 * wl, lane); hgrn_chunk<OUT>(a, wb, DLs, DLs + 128, DALL + (2 * wl) * 64, layer, h, lane, r0, U0, o[0], qf[0]); }
;     asm volatile("" ::: "memory"); __builtin_amdgcn_sched_barrier(0); HG_LAUNDER();
;     { const HRaw r1 = hgrn_loadc<OUT>(a, bh, c, 2 * wl + 1, lane); hgrn_chunk<OUT>(a, wb, DLs + 64, DLs + 192, DALL + (2 * wl + 1) * 64, layer, h, lane, r1, Up, o[1], qf[1]); }
.LBB0_460:
	s_and_b32 s3, s30, 31
	s_ashr_i32 s2, s30, 5
	s_xor_b32 s24, s3, 63
	s_and_b64 s[0:1], s[10:11], exec
	s_cselect_b32 s31, s3, s24
	s_ashr_i32 s0, s30, 7
	s_ashr_i32 s1, s0, 31
	s_lshl_b64 s[24:25], s[0:1], 13
	s_lshl_b32 s0, s31, 7
	s_or_b32 s24, s24, s0
	v_or_b32_e32 v2, s24, v142
	v_mov_b64_e32 v[0:1], s[60:61]
	s_lshl_b32 s37, s2, 6
	v_mad_u64_u32 v[0:1], s[0:1], v2, s93, v[0:1]
	v_mov_b32_e32 v2, 0x1c00
	s_and_b32 s0, s37, 0xc0
	v_mad_i32_i24 v1, s25, v2, v1
	s_lshl_b32 s62, s0, 1
	v_lshl_add_u64 v[0:1], v[0:1], 0, s[62:63]
	v_lshl_add_u64 v[8:9], v[0:1], 0, v[220:221]
	v_add_co_u32_e32 v12, vcc, s55, v8
	s_nop 1
	v_addc_co_u32_e32 v13, vcc, 0, v9, vcc
	s_barrier
	s_cmpk_lg_i32 s92, 0x100
	s_cbranch_scc1 .Lmy_hq_norm
	s_bitcmp0_b32 s30, 4
	s_cbranch_scc1 .Lmy_hq_norm
	s_and_b32 s38, s2, 3
	s_andn2_b64 vcc, exec, s[4:5]
	s_waitcnt vmcnt(0) lgkmcnt(0)
	ds_write_b128 v143, v[200:203]
	ds_write_b128 v143, v[204:207] offset:2304
	ds_write_b128 v143, v[208:211] offset:1152
	ds_write_b128 v143, v[212:215] offset:3456
	v_mov_b32_e32 v160, v216
	v_mov_b32_e32 v161, v217
	v_mov_b32_e32 v162, v218
	v_mov_b32_e32 v163, v219
	v_mov_b32_e32 v164, v222
	v_mov_b32_e32 v165, v223
	v_mov_b32_e32 v166, v224
	v_mov_b32_e32 v167, v225
	v_mov_b32_e32 v168, v226
	v_mov_b32_e32 v169, v227
	v_mov_b32_e32 v170, v228
	v_mov_b32_e32 v171, v229
	v_mov_b32_e32 v172, v230
	v_mov_b32_e32 v173, v231
	v_mov_b32_e32 v174, v232
	v_mov_b32_e32 v175, v233
	s_branch .Lmy_hq_join

; #define LAS __attribute__((address_space(3)))
; __device__ __forceinline__ float bf1(bf16 h) { return __uint_as_float(((unsigned)h) << 16); }
; __device__ __forceinline__ float sigmf(float v) { return __builtin_amdgcn_rcpf(1.0f + __builtin_amdgcn_exp2f(-1.4426950408889634f * v)); }
; template <bool OUT> __device__ __forceinline__ void hgrn_chunk(const PA& a, LAS unsigned char* wb, LAS float* DLk, LAS float* E7k, LAS float* DALLk, int layer, int h, int lane, const HRaw& raw, ...
;     ...
;         {
;             u16 vr[16];
; #pragma unroll
;             for (int t = 0; t < 16; ++t) vr[t] = RV[t * 72 + lane];
;             const v4u w0 = {(unsigned)vr[0] | ((unsigned)vr[1] << 16), (unsigned)vr[2] | ((unsigned)vr[3] << 16), (unsigned)vr[4] | ((unsigned)vr[5] << 16), (unsigned)vr[6] | ((unsigned)vr[7] << 16)};
;             const v4u w1 = {(unsigned)vr[8] | ((unsigned)vr[9] << 16), (unsigned)vr[10] | ((unsigned)vr[11] << 16), (unsigned)vr[12] | ((unsigned)vr[13] << 16), (unsigned)vr[14] | ((unsigned)vr[15] << 16)};
;             *(LAS v4u*)(VT + lane * 24) = w0; *(LAS v4u*)(VT + lane * 24 + 8) = w1;
;         }
;         float cum[16], kk[16]; float run = 0.f;
; #pragma unroll
;         for (int t = 0; t < 16; ++t) { const float sg = sigmf(bf1(RF[t * 72 + lane])); const float f = lb + (1.f - lb) * sg; kk[t] = (1.f - lb) * (1.f - sg); run += fmaxf(__logf(f), -69.f); cum[t] = run; }
.LBB0_462:
	s_nop 0
	v_mov_b32_e32 v177, v1
	ds_read_u16 v2, v146 offset:2304
	ds_read_u16 v6, v146 offset:2448
	ds_read_u16 v3, v146 offset:2592
	ds_read_u16 v7, v146 offset:2736
	ds_read_u16 v4, v146 offset:2880
	ds_read_u16 v8, v146 offset:3024
	ds_read_u16 v5, v146 offset:3168
	ds_read_u16 v9, v146 offset:3312
	ds_read_u16 v10, v146 offset:3456
	ds_read_u16 v11, v146 offset:3600
	ds_read_u16 v12, v146 offset:3744
	ds_read_u16 v13, v146 offset:3888
	ds_read_u16 v14, v146 offset:4032
	ds_read_u16 v15, v146 offset:4176
	ds_read_u16 v16, v146 offset:4320
	ds_read_u16 v17, v146 offset:4464
	s_mov_b32 s2, 0x5040100
	s_waitcnt lgkmcnt(8)
	v_perm_b32 v5, v9, v5, s2
	v_perm_b32 v4, v8, v4, s2
	v_perm_b32 v3, v7, v3, s2
	v_perm_b32 v2, v6, v2, s2
	s_waitcnt lgkmcnt(0)
	v_perm_b32 v9, v17, v16, s2
	v_perm_b32 v8, v15, v14, s2
	v_perm_b32 v7, v13, v12, s2
	v_perm_b32 v6, v11, v10, s2
	ds_write_b128 v147, v[2:5] offset:7680
	ds_write_b128 v147, v[6:9] offset:7696
	ds_read_u16 v3, v148
	ds_read_u16 v184, v148 offset:144
	ds_read_u16 v185, v148 offset:288
	ds_read_u16 v186, v148 offset:432
	ds_read_u16 v187, v148 offset:576
	ds_read_u16 v188, v148 offset:720
	ds_read_u16 v189, v148 offset:864
	ds_read_u16 v190, v148 offset:1008
	ds_read_u16 v191, v148 offset:1152
	ds_read_u16 v192, v148 offset:1296
	ds_read_u16 v193, v148 offset:1440
	ds_read_u16 v194, v148 offset:1584
	ds_read_u16 v195, v148 offset:1728
	ds_read_u16 v196, v148 offset:1872
	ds_read_u16 v197, v148 offset:2016
	ds_read_u16 v198, v148 offset:2160
	v_sub_f32_e32 v2, 1.0, v1
	s_waitcnt lgkmcnt(0)
	v_lshlrev_b32_e32 v3, 16, v3
	v_mul_f32_e32 v3, 0xbfb8aa3b, v3
	v_exp_f32_e32 v3, v3
	s_nop 0
	v_add_f32_e32 v3, 1.0, v3
	v_rcp_f32_e32 v4, v3
	s_nop 0
	v_fma_f32 v3, v2, v4, v1
	v_cmp_gt_f32_e32 vcc, s27, v3
	s_nop 1
	v_cndmask_b32_e64 v5, 0, 32, vcc
	v_ldexp_f32 v3, v3, v5
	v_log_f32_e32 v3, v3
	s_nop 0
	v_mul_f32_e32 v5, 0x3f317217, v3
	v_fma_f32 v5, v3, s80, -v5
	v_fmac_f32_e32 v5, 0x3377d1cf, v3
	v_fmac_f32_e32 v5, 0x3f317217, v3
	v_cmp_lt_f32_e64 s[42:43], |v3|, s81
	s_nop 1
	v_cndmask_b32_e64 v3, v3, v5, s[42:43]
	v_cndmask_b32_e32 v5, 0, v238, vcc
	v_sub_f32_e32 v3, v3, v5
	v_max_f32_e32 v3, 0xc28a0000, v3
	v_add_f32_e32 v3, 0, v3
	s_waitcnt lgkmcnt(0)
	v_lshlrev_b32_e32 v5, 16, v184
	v_mul_f32_e32 v5, 0xbfb8aa3b, v5
	v_exp_f32_e32 v5, v5
	s_nop 0
	v_add_f32_e32 v5, 1.0, v5
	v_rcp_f32_e32 v6, v5
	s_nop 0
	v_fma_f32 v5, v2, v6, v1
	v_cmp_gt_f32_e32 vcc, s27, v5
	s_nop 1
	v_cndmask_b32_e64 v7, 0, 32, vcc
	v_ldexp_f32 v5, v5, v7
	v_log_f32_e32 v5, v5
	s_nop 0
	v_mul_f32_e32 v7, 0x3f317217, v5
	v_fma_f32 v7, v5, s80, -v7
	v_fmac_f32_e32 v7, 0x3377d1cf, v5
	v_fmac_f32_e32 v7, 0x3f317217, v5
	v_cmp_lt_f32_e64 s[42:43], |v5|, s81
	s_nop 1
	v_cndmask_b32_e64 v5, v5, v7, s[42:43]
	v_cndmask_b32_e32 v7, 0, v238, vcc
	v_sub_f32_e32 v5, v5, v7
	v_max_f32_e32 v5, 0xc28a0000, v5
	v_add_f32_e32 v20, v3, v5
	s_waitcnt lgkmcnt(0)
	v_lshlrev_b32_e32 v5, 16, v185
	v_mul_f32_e32 v5, 0xbfb8aa3b, v5
	v_exp_f32_e32 v5, v5
	s_nop 0
	v_add_f32_e32 v5, 1.0, v5
	v_rcp_f32_e32 v5, v5
	s_nop 0
	v_fma_f32 v7, v2, v5, v1
	v_cmp_gt_f32_e32 vcc, s27, v7
	v_pk_add_f32 v[4:5], v[4:5], 1.0 op_sel_hi:[1,0] neg_lo:[1,0] neg_hi:[1,0]
	s_nop 0
	v_cndmask_b32_e64 v8, 0, 32, vcc
	v_ldexp_f32 v7, v7, v8
	v_log_f32_e32 v7, v7
	s_nop 0
	v_mul_f32_e32 v8, 0x3f317217, v7
	v_fma_f32 v8, v7, s80, -v8
	v_fmac_f32_e32 v8, 0x3377d1cf, v7
	v_fmac_f32_e32 v8, 0x3f317217, v7
	v_cmp_lt_f32_e64 s[42:43], |v7|, s81
	s_nop 1
	v_cndmask_b32_e64 v7, v7, v8, s[42:43]
	v_cndmask_b32_e32 v8, 0, v238, vcc
	v_sub_f32_e32 v7, v7, v8
	v_max_f32_e32 v7, 0xc28a0000, v7
	v_add_f32_e32 v21, v20, v7
	s_waitcnt lgkmcnt(0)
	v_lshlrev_b32_e32 v7, 16, v186
	v_mul_f32_e32 v7, 0xbfb8aa3b, v7
	v_exp_f32_e32 v7, v7
	s_nop 0
	v_add_f32_e32 v7, 1.0, v7
	v_rcp_f32_e32 v7, v7
	s_nop 0
	v_fma_f32 v8, v2, v7, v1
	v_cmp_gt_f32_e32 vcc, s27, v8
	v_pk_add_f32 v[6:7], v[6:7], 1.0 op_sel_hi:[1,0] neg_lo:[1,0] neg_hi:[1,0]
	s_nop 0
	v_cndmask_b32_e64 v9, 0, 32, vcc
	v_ldexp_f32 v8, v8, v9
	v_log_f32_e32 v8, v8
	s_nop 0
	v_mul_f32_e32 v9, 0x3f317217, v8
	v_fma_f32 v9, v8, s80, -v9
	v_fmac_f32_e32 v9, 0x3377d1cf, v8
	v_fmac_f32_e32 v9, 0x3f317217, v8
	v_cmp_lt_f32_e64 s[42:43], |v8|, s81
	s_nop 1
	v_cndmask_b32_e64 v8, v8, v9, s[42:43]
	v_cndmask_b32_e32 v9, 0, v238, vcc
	v_sub_f32_e32 v8, v8, v9
	v_max_f32_e32 v8, 0xc28a0000, v8
	v_add_f32_e32 v22, v21, v8
	s_waitcnt lgkmcnt(0)
	v_lshlrev_b32_e32 v8, 16, v187
	v_mul_f32_e32 v8, 0xbfb8aa3b, v8
	v_exp_f32_e32 v8, v8
	s_nop 0
	v_add_f32_e32 v8, 1.0, v8
	v_rcp_f32_e32 v8, v8
	s_nop 0
	v_fma_f32 v9, v2, v8, v1
	v_cmp_gt_f32_e32 vcc, s27, v9
	s_nop 1
	v_cndmask_b32_e64 v10, 0, 32, vcc
	v_ldexp_f32 v9, v9, v10
	v_log_f32_e32 v9, v9
	s_nop 0
	v_mul_f32_e32 v10, 0x3f317217, v9
	v_fma_f32 v10, v9, s80, -v10
	v_fmac_f32_e32 v10, 0x3377d1cf, v9
	v_fmac_f32_e32 v10, 0x3f317217, v9
	v_cmp_lt_f32_e64 s[42:43], |v9|, s81
	s_nop 1
	v_cndmask_b32_e64 v9, v9, v10, s[42:43]
	v_cndmask_b32_e32 v10, 0, v238, vcc
	v_sub_f32_e32 v9, v9, v10
	v_max_f32_e32 v9, 0xc28a0000, v9
	v_add_f32_e32 v23, v22, v9
	s_waitcnt lgkmcnt(0)
	v_lshlrev_b32_e32 v9, 16, v188
	v_mul_f32_e32 v9, 0xbfb8aa3b, v9
	v_exp_f32_e32 v9, v9
	s_nop 0
	v_add_f32_e32 v9, 1.0, v9
	v_rcp_f32_e32 v10, v9
	s_nop 0
	v_fma_f32 v9, v2, v10, v1
	v_cmp_gt_f32_e32 vcc, s27, v9
	s_nop 1
	v_cndmask_b32_e64 v11, 0, 32, vcc
	v_ldexp_f32 v9, v9, v11
	v_log_f32_e32 v9, v9
	s_nop 0
	v_mul_f32_e32 v11, 0x3f317217, v9
	v_fma_f32 v11, v9, s80, -v11
	v_fmac_f32_e32 v11, 0x3377d1cf, v9
	v_fmac_f32_e32 v11, 0x3f317217, v9
	v_cmp_lt_f32_e64 s[42:43], |v9|, s81
	s_nop 1
	v_cndmask_b32_e64 v9, v9, v11, s[42:43]
	v_cndmask_b32_e32 v11, 0, v238, vcc
	v_sub_f32_e32 v9, v9, v11
	v_max_f32_e32 v9, 0xc28a0000, v9
	v_add_f32_e32 v24, v23, v9
	s_waitcnt lgkmcnt(0)
; __device__ __forceinline__ float bf1(bf16 h) { return __uint_as_float(((unsigned)h) << 16); }
; __device__ __forceinline__ float sigmf(float v) { return __builtin_amdgcn_rcpf(1.0f + __builtin_amdgcn_exp2f(-1.4426950408889634f * v)); }
; template <bool OUT> __device__ __forceinline__ void hgrn_chunk(const PA& a, LAS unsigned char* wb, LAS float* DLk, LAS float* E7k, LAS float* DALLk, int layer, int h, int lane, const HRaw& raw, ...
;     ...
;         for (int t = 0; t < 16; ++t) { const float sg = sigmf(bf1(RF[t * 72 + lane])); const float f = lb + (1.f - lb) * sg; kk[t] = (1.f - lb) * (1.f - sg); run += fmaxf(__logf(f), -69.f); cum[t] = run; }
	v_lshlrev_b32_e32 v9, 16, v189
	v_mul_f32_e32 v9, 0xbfb8aa3b, v9
	v_exp_f32_e32 v9, v9
	s_nop 0
	v_add_f32_e32 v9, 1.0, v9
	v_rcp_f32_e32 v9, v9
	s_nop 0
	v_fma_f32 v11, v2, v9, v1
	v_cmp_gt_f32_e32 vcc, s27, v11
	v_pk_add_f32 v[8:9], v[8:9], 1.0 op_sel_hi:[1,0] neg_lo:[1,0] neg_hi:[1,0]
	s_nop 0
	v_cndmask_b32_e64 v12, 0, 32, vcc
	v_ldexp_f32 v11, v11, v12
	v_log_f32_e32 v11, v11
	s_nop 0
	v_mul_f32_e32 v12, 0x3f317217, v11
	v_fma_f32 v12, v11, s80, -v12
	v_fmac_f32_e32 v12, 0x3377d1cf, v11
	v_fmac_f32_e32 v12, 0x3f317217, v11
	v_cmp_lt_f32_e64 s[42:43], |v11|, s81
	s_nop 1
	v_cndmask_b32_e64 v11, v11, v12, s[42:43]
	v_cndmask_b32_e32 v12, 0, v238, vcc
	v_sub_f32_e32 v11, v11, v12
	v_max_f32_e32 v11, 0xc28a0000, v11
	v_add_f32_e32 v25, v24, v11
	s_waitcnt lgkmcnt(0)
	v_lshlrev_b32_e32 v11, 16, v190
	v_mul_f32_e32 v11, 0xbfb8aa3b, v11
	v_exp_f32_e32 v11, v11
	s_nop 0
	v_add_f32_e32 v11, 1.0, v11
	v_rcp_f32_e32 v11, v11
	s_nop 0
	v_fma_f32 v12, v2, v11, v1
	v_cmp_gt_f32_e32 vcc, s27, v12
	v_pk_add_f32 v[10:11], v[10:11], 1.0 op_sel_hi:[1,0] neg_lo:[1,0] neg_hi:[1,0]
	s_nop 0
	v_cndmask_b32_e64 v13, 0, 32, vcc
	v_ldexp_f32 v12, v12, v13
	v_log_f32_e32 v12, v12
	s_nop 0
	v_mul_f32_e32 v13, 0x3f317217, v12
	v_fma_f32 v13, v12, s80, -v13
	v_fmac_f32_e32 v13, 0x3377d1cf, v12
	v_fmac_f32_e32 v13, 0x3f317217, v12
	v_cmp_lt_f32_e64 s[42:43], |v12|, s81
	s_nop 1
	v_cndmask_b32_e64 v12, v12, v13, s[42:43]
	v_cndmask_b32_e32 v13, 0, v238, vcc
	v_sub_f32_e32 v12, v12, v13
	v_max_f32_e32 v12, 0xc28a0000, v12
	v_add_f32_e32 v26, v25, v12
	s_waitcnt lgkmcnt(0)
	v_lshlrev_b32_e32 v12, 16, v191
	v_mul_f32_e32 v12, 0xbfb8aa3b, v12
	v_exp_f32_e32 v12, v12
	s_nop 0
	v_add_f32_e32 v12, 1.0, v12
	v_rcp_f32_e32 v12, v12
	s_nop 0
	v_fma_f32 v13, v2, v12, v1
	v_cmp_gt_f32_e32 vcc, s27, v13
	s_nop 1
	v_cndmask_b32_e64 v14, 0, 32, vcc
	v_ldexp_f32 v13, v13, v14
	v_log_f32_e32 v13, v13
	s_nop 0
	v_mul_f32_e32 v14, 0x3f317217, v13
	v_fma_f32 v14, v13, s80, -v14
	v_fmac_f32_e32 v14, 0x3377d1cf, v13
	v_fmac_f32_e32 v14, 0x3f317217, v13
	v_cmp_lt_f32_e64 s[42:43], |v13|, s81
	s_nop 1
	v_cndmask_b32_e64 v13, v13, v14, s[42:43]
	v_cndmask_b32_e32 v14, 0, v238, vcc
	v_sub_f32_e32 v13, v13, v14
	v_max_f32_e32 v13, 0xc28a0000, v13
	v_add_f32_e32 v27, v26, v13
	s_waitcnt lgkmcnt(0)
	v_lshlrev_b32_e32 v13, 16, v192
	v_mul_f32_e32 v13, 0xbfb8aa3b, v13
	v_exp_f32_e32 v13, v13
	s_nop 0
	v_add_f32_e32 v13, 1.0, v13
	v_rcp_f32_e32 v14, v13
	s_nop 0
	v_fma_f32 v13, v2, v14, v1
	v_cmp_gt_f32_e32 vcc, s27, v13
	s_nop 1
	v_cndmask_b32_e64 v15, 0, 32, vcc
	v_ldexp_f32 v13, v13, v15
	v_log_f32_e32 v13, v13
	s_nop 0
	v_mul_f32_e32 v15, 0x3f317217, v13
	v_fma_f32 v15, v13, s80, -v15
	v_fmac_f32_e32 v15, 0x3377d1cf, v13
	v_fmac_f32_e32 v15, 0x3f317217, v13
	v_cmp_lt_f32_e64 s[42:43], |v13|, s81
	s_nop 1
	v_cndmask_b32_e64 v13, v13, v15, s[42:43]
	v_cndmask_b32_e32 v15, 0, v238, vcc
	v_sub_f32_e32 v13, v13, v15
	v_max_f32_e32 v13, 0xc28a0000, v13
	v_add_f32_e32 v28, v27, v13
	s_waitcnt lgkmcnt(0)
	v_lshlrev_b32_e32 v13, 16, v193
	v_mul_f32_e32 v13, 0xbfb8aa3b, v13
	v_exp_f32_e32 v13, v13
	s_nop 0
	v_add_f32_e32 v13, 1.0, v13
	v_rcp_f32_e32 v13, v13
	s_nop 0
	v_fma_f32 v15, v2, v13, v1
	v_cmp_gt_f32_e32 vcc, s27, v15
	s_nop 1
	v_cndmask_b32_e64 v16, 0, 32, vcc
	v_ldexp_f32 v15, v15, v16
	v_log_f32_e32 v15, v15
	s_nop 0
	v_mul_f32_e32 v16, 0x3f317217, v15
	v_fma_f32 v16, v15, s80, -v16
	v_fmac_f32_e32 v16, 0x3377d1cf, v15
	v_fmac_f32_e32 v16, 0x3f317217, v15
	v_cmp_lt_f32_e64 s[42:43], |v15|, s81
	s_nop 1
	v_cndmask_b32_e64 v15, v15, v16, s[42:43]
	v_cndmask_b32_e32 v16, 0, v238, vcc
	v_sub_f32_e32 v15, v15, v16
	v_max_f32_e32 v15, 0xc28a0000, v15
	v_add_f32_e32 v29, v28, v15
	s_waitcnt lgkmcnt(0)
	v_lshlrev_b32_e32 v15, 16, v194
	v_mul_f32_e32 v15, 0xbfb8aa3b, v15
	v_exp_f32_e32 v15, v15
	s_nop 0
	v_add_f32_e32 v15, 1.0, v15
	v_rcp_f32_e32 v15, v15
	s_nop 0
	v_fma_f32 v16, v2, v15, v1
	v_cmp_gt_f32_e32 vcc, s27, v16
	s_nop 1
	v_cndmask_b32_e64 v17, 0, 32, vcc
	v_ldexp_f32 v16, v16, v17
	v_log_f32_e32 v16, v16
	s_nop 0
	v_mul_f32_e32 v17, 0x3f317217, v16
	v_fma_f32 v17, v16, s80, -v17
	v_fmac_f32_e32 v17, 0x3377d1cf, v16
	v_fmac_f32_e32 v17, 0x3f317217, v16
	v_cmp_lt_f32_e64 s[42:43], |v16|, s81
	s_nop 1
	v_cndmask_b32_e64 v16, v16, v17, s[42:43]
	v_cndmask_b32_e32 v17, 0, v238, vcc
	v_sub_f32_e32 v16, v16, v17
	v_max_f32_e32 v16, 0xc28a0000, v16
	v_add_f32_e32 v30, v29, v16
	s_waitcnt lgkmcnt(0)
	v_lshlrev_b32_e32 v16, 16, v195
	v_mul_f32_e32 v16, 0xbfb8aa3b, v16
	v_exp_f32_e32 v16, v16
	s_nop 0
	v_add_f32_e32 v16, 1.0, v16
	v_rcp_f32_e32 v16, v16
	s_nop 0
	v_fma_f32 v17, v2, v16, v1
	v_cmp_gt_f32_e32 vcc, s27, v17
	s_nop 1
	v_cndmask_b32_e64 v18, 0, 32, vcc
	v_ldexp_f32 v17, v17, v18
	v_log_f32_e32 v17, v17
	s_nop 0
	v_mul_f32_e32 v18, 0x3f317217, v17
	v_fma_f32 v18, v17, s80, -v18
	v_fmac_f32_e32 v18, 0x3377d1cf, v17
	v_fmac_f32_e32 v18, 0x3f317217, v17
	v_cmp_lt_f32_e64 s[42:43], |v17|, s81
	s_nop 1
	v_cndmask_b32_e64 v17, v17, v18, s[42:43]
	v_cndmask_b32_e32 v18, 0, v238, vcc
	v_sub_f32_e32 v17, v17, v18
	v_max_f32_e32 v17, 0xc28a0000, v17
	v_add_f32_e32 v31, v30, v17
	s_waitcnt lgkmcnt(0)
	v_lshlrev_b32_e32 v17, 16, v196
	v_mul_f32_e32 v17, 0xbfb8aa3b, v17
	v_exp_f32_e32 v17, v17
	s_nop 0
	v_add_f32_e32 v17, 1.0, v17
	v_rcp_f32_e32 v18, v17
	s_nop 0
	v_fma_f32 v17, v2, v18, v1
	v_cmp_gt_f32_e32 vcc, s27, v17
	s_nop 1
	v_cndmask_b32_e64 v19, 0, 32, vcc
	v_ldexp_f32 v17, v17, v19
	v_log_f32_e32 v17, v17
	s_nop 0
	v_mul_f32_e32 v19, 0x3f317217, v17
	v_fma_f32 v19, v17, s80, -v19
	v_fmac_f32_e32 v19, 0x3377d1cf, v17
	v_fmac_f32_e32 v19, 0x3f317217, v17
	v_cmp_lt_f32_e64 s[42:43], |v17|, s81
	s_nop 1
	v_cndmask_b32_e64 v17, v17, v19, s[42:43]
	v_cndmask_b32_e32 v19, 0, v238, vcc
	v_sub_f32_e32 v17, v17, v19
	v_max_f32_e32 v17, 0xc28a0000, v17
	v_add_f32_e32 v32, v31, v17
	s_waitcnt lgkmcnt(0)
; #define LAS __attribute__((address_space(3)))
; #define LDS_WAIT() asm volatile("s_waitcnt lgkmcnt(0)" ::: "memory")
; __device__ __forceinline__ unsigned f2bf(float f) { unsigned u = __builtin_bit_cast(unsigned, f); return (u + 0x7fffu + ((u >> 16) & 1u)) >> 16; }
; __device__ __forceinline__ float bf1(bf16 h) { return __uint_as_float(((unsigned)h) << 16); }
; __device__ __forceinline__ float sigmf(float v) { return __builtin_amdgcn_rcpf(1.0f + __builtin_amdgcn_exp2f(-1.4426950408889634f * v)); }
; __device__ __forceinline__ float siluf(float v) { return v * sigmf(v); }
; __device__ __forceinline__ bf16x8 pk8(const float* v) { v4u w = {pk2(v[0], v[1]), pk2(v[2], v[3]), pk2(v[4], v[5]), pk2(v[6], v[7])}; return __builtin_bit_cast(bf16x8, w); }
; template <bool OUT> __device__ __forceinline__ void hgrn_chunk(const PA& a, LAS unsigned char* wb, LAS float* DLk, LAS float* E7k, LAS float* DALLk, int layer, int h, int lane, const HRaw& raw, ...
;     ...
;         for (int t = 0; t < 16; ++t) { const float sg = sigmf(bf1(RF[t * 72 + lane])); const float f = lb + (1.f - lb) * sg; kk[t] = (1.f - lb) * (1.f - sg); run += fmaxf(__logf(f), -69.f); cum[t] = run; }
;         const float cl = cum[15], c7 = cum[7];
;         DLk[lane] = __expf(cl);
;         if (OUT) E7k[lane] = __expf(c7); else DALLk[lane] = cl;
;         if (OUT) {
;             float qv[16];
; #pragma unroll
;             for (int t = 0; t < 16; ++t) qv[t] = bf1(RQ[t * 72 + lane]);
;             LDS_WAIT();
; #pragma unroll
;             for (int t = 0; t < 16; ++t) {
;                 QT[t * 72 + lane] = (bf16)f2bf(siluf(qv[t]) * __expf(fminf(cum[t] - c7, 60.f)));
;                 KT[t * 72 + lane] = (bf16)f2bf(kk[t] * __expf(fminf(c7 - cum[t], 60.f)));
;             }
;         }
;         LDS_WAIT();
;         float kh[16];
; #pragma unroll
;         for (int t = 0; t < 16; ++t) kh[t] = kk[t] * __expf(cl - cum[t]);
;         *(LAS bf16x8*)(KHT + lane * 24) = pk8(kh); *(LAS bf16x8*)(KHT + lane * 24 + 8) = pk8(kh + 8);
	v_lshlrev_b32_e32 v17, 16, v197
	v_mul_f32_e32 v17, 0xbfb8aa3b, v17
	v_exp_f32_e32 v17, v17
	s_nop 0
	v_add_f32_e32 v17, 1.0, v17
	v_rcp_f32_e32 v17, v17
	s_nop 0
	v_fma_f32 v19, v2, v17, v1
	v_cmp_gt_f32_e32 vcc, s27, v19
	s_nop 1
	v_cndmask_b32_e64 v33, 0, 32, vcc
	v_ldexp_f32 v19, v19, v33
	v_log_f32_e32 v19, v19
	s_nop 0
	v_mul_f32_e32 v33, 0x3f317217, v19
	v_fma_f32 v33, v19, s80, -v33
	v_fmac_f32_e32 v33, 0x3377d1cf, v19
	v_fmac_f32_e32 v33, 0x3f317217, v19
	v_cmp_lt_f32_e64 s[42:43], |v19|, s81
	s_nop 1
	v_cndmask_b32_e64 v19, v19, v33, s[42:43]
	v_cndmask_b32_e32 v33, 0, v238, vcc
	v_sub_f32_e32 v19, v19, v33
	v_max_f32_e32 v19, 0xc28a0000, v19
	v_add_f32_e32 v33, v32, v19
	s_waitcnt lgkmcnt(0)
	v_lshlrev_b32_e32 v19, 16, v198
	v_mul_f32_e32 v19, 0xbfb8aa3b, v19
	v_exp_f32_e32 v19, v19
	s_nop 0
	v_add_f32_e32 v19, 1.0, v19
	v_rcp_f32_e32 v19, v19
	s_nop 0
	v_fmac_f32_e32 v1, v2, v19
	v_cmp_gt_f32_e32 vcc, s27, v1
	s_nop 1
	v_cndmask_b32_e64 v34, 0, 32, vcc
	v_ldexp_f32 v1, v1, v34
	v_log_f32_e32 v1, v1
	s_nop 0
	v_mul_f32_e32 v34, 0x3f317217, v1
	v_fma_f32 v34, v1, s80, -v34
	v_fmac_f32_e32 v34, 0x3377d1cf, v1
	v_fmac_f32_e32 v34, 0x3f317217, v1
	v_cmp_lt_f32_e64 s[42:43], |v1|, s81
	s_nop 1
	v_cndmask_b32_e64 v1, v1, v34, s[42:43]
	v_cndmask_b32_e32 v34, 0, v238, vcc
	v_sub_f32_e32 v1, v1, v34
	v_max_f32_e32 v1, 0xc28a0000, v1
	v_add_f32_e32 v1, v33, v1
	v_mul_f32_e32 v34, 0x3fb8aa3b, v1
	v_exp_f32_e32 v34, v34
	v_sub_f32_e32 v3, v1, v3
	v_mul_f32_e32 v3, 0x3fb8aa3b, v3
	ds_write_b32 v149, v34 offset:11520
	ds_write_b32 v150, v1
	v_exp_f32_e32 v34, v3
	v_sub_f32_e32 v3, v1, v20
	v_mul_f32_e32 v3, 0x3fb8aa3b, v3
	v_exp_f32_e32 v20, v3
	v_sub_f32_e32 v3, v1, v21
	v_mul_f32_e32 v3, 0x3fb8aa3b, v3
	v_exp_f32_e32 v35, v3
	v_sub_f32_e32 v3, v1, v22
	v_mul_f32_e32 v3, 0x3fb8aa3b, v3
	v_exp_f32_e32 v21, v3
	v_sub_f32_e32 v3, v1, v23
	v_mul_f32_e32 v3, 0x3fb8aa3b, v3
	v_exp_f32_e32 v22, v3
	v_sub_f32_e32 v3, v1, v24
	v_mul_f32_e32 v3, 0x3fb8aa3b, v3
	v_exp_f32_e32 v24, v3
	v_sub_f32_e32 v3, v1, v25
	v_mul_f32_e32 v3, 0x3fb8aa3b, v3
	v_exp_f32_e32 v23, v3
	v_sub_f32_e32 v3, v1, v26
	v_mul_f32_e32 v3, 0x3fb8aa3b, v3
	v_exp_f32_e32 v25, v3
	v_sub_f32_e32 v3, v1, v27
	v_mul_f32_e32 v3, 0x3fb8aa3b, v3
	v_exp_f32_e32 v26, v3
	v_sub_f32_e32 v3, v1, v28
	v_mul_f32_e32 v3, 0x3fb8aa3b, v3
	v_exp_f32_e32 v28, v3
	v_sub_f32_e32 v3, v1, v29
	v_mul_f32_e32 v3, 0x3fb8aa3b, v3
	v_exp_f32_e32 v27, v3
	v_sub_f32_e32 v3, v1, v30
	v_mul_f32_e32 v3, 0x3fb8aa3b, v3
	v_exp_f32_e32 v29, v3
	v_sub_f32_e32 v3, v1, v31
	v_mul_f32_e32 v3, 0x3fb8aa3b, v3
	v_exp_f32_e32 v30, v3
	v_sub_f32_e32 v3, v1, v32
	v_mul_f32_e32 v3, 0x3fb8aa3b, v3
	v_exp_f32_e32 v32, v3
	v_sub_f32_e32 v3, v1, v33
	v_mul_f32_e32 v3, 0x3fb8aa3b, v3
	v_sub_f32_e32 v1, v1, v1
	v_pk_mul_f32 v[6:7], v[2:3], v[6:7] op_sel_hi:[0,1]
	v_pk_mul_f32 v[10:11], v[2:3], v[10:11] op_sel_hi:[0,1]
	v_mul_f32_e32 v1, 0x3fb8aa3b, v1
	v_pk_mul_f32 v[4:5], v[2:3], v[4:5] op_sel_hi:[0,1]
	v_pk_mul_f32 v[6:7], v[6:7], v[20:21]
	v_pk_mul_f32 v[8:9], v[2:3], v[8:9] op_sel_hi:[0,1]
	v_pk_mul_f32 v[10:11], v[10:11], v[24:25]
	v_exp_f32_e32 v31, v3
	v_exp_f32_e32 v33, v1
	v_pk_mul_f32 v[4:5], v[4:5], v[34:35]
	v_pk_mul_f32 v[8:9], v[8:9], v[22:23]
	v_bfe_u32 v1, v11, 16, 1
	v_bfe_u32 v3, v10, 16, 1
	v_bfe_u32 v20, v7, 16, 1
	v_bfe_u32 v21, v6, 16, 1
	v_add3_u32 v21, v6, v21, s73
	v_add3_u32 v20, v7, v20, s73
	v_add3_u32 v3, v10, v3, s73
	v_add3_u32 v1, v11, v1, s73
	v_bfe_u32 v6, v8, 16, 1
	v_bfe_u32 v7, v9, 16, 1
	v_bfe_u32 v10, v4, 16, 1
	v_bfe_u32 v11, v5, 16, 1
	v_add3_u32 v7, v9, v7, s73
	v_add3_u32 v6, v8, v6, s73
	v_add3_u32 v5, v5, v11, s73
	v_add3_u32 v4, v4, v10, s73
	v_lshrrev_b32_e32 v6, 16, v6
	v_lshrrev_b32_e32 v7, 16, v7
	v_lshrrev_b32_e32 v4, 16, v4
	v_lshrrev_b32_e32 v5, 16, v5
	v_and_or_b32 v7, v1, s26, v7
	v_and_or_b32 v6, v3, s26, v6
	v_and_or_b32 v5, v20, s26, v5
	v_and_or_b32 v4, v21, s26, v4
	s_waitcnt lgkmcnt(0)
	ds_write_b128 v151, v[4:7] offset:4608
	v_pk_add_f32 v[4:5], v[12:13], 1.0 op_sel_hi:[1,0] neg_lo:[1,0] neg_hi:[1,0]
	v_pk_add_f32 v[6:7], v[14:15], 1.0 op_sel_hi:[1,0] neg_lo:[1,0] neg_hi:[1,0]
	v_pk_add_f32 v[8:9], v[16:17], 1.0 op_sel_hi:[1,0] neg_lo:[1,0] neg_hi:[1,0]
	v_pk_add_f32 v[10:11], v[18:19], 1.0 op_sel_hi:[1,0] neg_lo:[1,0] neg_hi:[1,0]
	v_pk_mul_f32 v[4:5], v[2:3], v[4:5] op_sel_hi:[0,1]
	v_pk_mul_f32 v[6:7], v[2:3], v[6:7] op_sel_hi:[0,1]
	v_pk_mul_f32 v[8:9], v[2:3], v[8:9] op_sel_hi:[0,1]
	v_pk_mul_f32 v[2:3], v[2:3], v[10:11] op_sel_hi:[0,1]
	v_pk_mul_f32 v[6:7], v[6:7], v[28:29]
	v_pk_mul_f32 v[2:3], v[2:3], v[32:33]
	v_pk_mul_f32 v[4:5], v[4:5], v[26:27]
	v_pk_mul_f32 v[8:9], v[8:9], v[30:31]
	v_bfe_u32 v1, v7, 16, 1
	v_bfe_u32 v10, v6, 16, 1
	v_bfe_u32 v11, v3, 16, 1
	v_bfe_u32 v12, v2, 16, 1
	v_add3_u32 v6, v6, v10, s73
	v_add3_u32 v1, v7, v1, s73
	v_add3_u32 v7, v2, v12, s73
	v_add3_u32 v10, v3, v11, s73
	v_bfe_u32 v2, v8, 16, 1
	v_bfe_u32 v3, v9, 16, 1
	v_bfe_u32 v11, v4, 16, 1
	v_bfe_u32 v12, v5, 16, 1
	v_add3_u32 v5, v5, v12, s73
	v_add3_u32 v4, v4, v11, s73
	v_add3_u32 v3, v9, v3, s73
	v_add3_u32 v2, v8, v2, s73
	v_lshrrev_b32_e32 v8, 16, v2
	v_lshrrev_b32_e32 v9, 16, v3
	v_lshrrev_b32_e32 v2, 16, v4
	v_lshrrev_b32_e32 v3, 16, v5
	v_and_or_b32 v3, v1, s26, v3
	v_and_or_b32 v2, v6, s26, v2
	v_and_or_b32 v5, v10, s26, v9
	v_and_or_b32 v4, v7, s26, v8
	ds_write_b128 v151, v[2:5] offset:4624
	s_waitcnt lgkmcnt(0)
; #define LAS __attribute__((address_space(3)))
; template <bool OUT> __device__ __forceinline__ HRaw hgrn_loadc(const PA& a, int bh, int c, int chunk, int lane) {
;     const bf16* pr = (const bf16*)(a.ws + WS_PROJ) + ((size_t)(bh >> 2) * T + (size_t)c * 128 + chunk * 16 + (lane >> 3)) * DIN + (bh & 3) * 64 + (lane & 7) * 8;
;     HRaw r;
; #pragma unroll
;     for (int k = 0; k < 2; ++k) { r.f[k] = *(const v4u*)(pr + (size_t)(8 * k) * DIN + 256); r.v[k] = *(const v4u*)(pr + (size_t)(8 * k) * DIN + 512);
;         if (OUT) { r.q[k] = *(const v4u*)(pr + (size_t)(8 * k) * DIN); } }
; template <bool OUT> __device__ __forceinline__ void hgrn_chunk(const PA& a, LAS unsigned char* wb, LAS float* DLk, LAS float* E7k, LAS float* DALLk, int layer, int h, int lane, const HRaw& raw, ...
;     ...
;     for (int nt = 0; nt < 4; ++nt) vfr[nt] = (q < 2) ? *(const LAS bf16x8*)(VT + (16 * nt + l15) * 24 + q * 8) : zero8;
; #pragma unroll
;     for (int mt = 0; mt < 4; ++mt) { const bf16x8 afr = (q < 2) ? *(const LAS bf16x8*)(KHT + (16 * mt + l15) * 24 + q * 8) : zero8;
; #pragma unroll
;         for (int nt = 0; nt < 4; ++nt) U[mt][nt] = __builtin_amdgcn_mfma_f32_16x16x32_bf16(afr, vfr[nt], (f32x4){0.f, 0.f, 0.f, 0.f}, 0, 0, 0); }
; template <bool OUT> __device__ __forceinline__ void hgrn_pair(const PA& a, LAS unsigned char* lds, int layer, int bh, int s, int wave, int lane) {
;     ...
;     { const HRaw r1 = hgrn_loadc<OUT>(a, bh, c, 2 * wl + 1, lane); hgrn_chunk<OUT>(a, wb, DLs + 64, DLs + 192, DALL + (2 * wl + 1) * 64, layer, h, lane, r1, Up, o[1], qf[1]); }
	v_mov_b32_e32 v1, 0
	v_mov_b32_e32 v2, 0
	v_mov_b32_e32 v3, 0
	s_and_saveexec_b64 s[2:3], s[40:41]
	ds_read_b128 v[0:3], v152 offset:7680
	s_or_b64 exec, exec, s[2:3]
	v_mov_b32_e32 v4, 0
	v_mov_b32_e32 v8, 0
	v_mov_b32_e32 v9, 0
	v_mov_b32_e32 v10, 0
	v_mov_b32_e32 v11, 0
	s_and_saveexec_b64 s[2:3], s[40:41]
	ds_read_b128 v[8:11], v152 offset:8448
	s_or_b64 exec, exec, s[2:3]
	v_mov_b32_e32 v5, 0
	v_mov_b32_e32 v6, 0
	v_mov_b32_e32 v7, 0
	s_and_saveexec_b64 s[2:3], s[40:41]
	ds_read_b128 v[4:7], v152 offset:9216
	s_or_b64 exec, exec, s[2:3]
	v_mov_b32_e32 v12, 0
	v_mov_b32_e32 v64, 0
	v_mov_b32_e32 v65, 0
	v_mov_b32_e32 v66, 0
	v_mov_b32_e32 v67, 0
	s_and_saveexec_b64 s[2:3], s[40:41]
	ds_read_b128 v[64:67], v152 offset:9984
	s_or_b64 exec, exec, s[2:3]
	v_mov_b32_e32 v13, 0
	v_mov_b32_e32 v14, 0
	v_mov_b32_e32 v15, 0
	s_and_saveexec_b64 s[2:3], s[40:41]
	ds_read_b128 v[12:15], v152 offset:4608
	s_or_b64 exec, exec, s[2:3]
	s_waitcnt lgkmcnt(0)
	v_mfma_f32_16x16x32_bf16 v[60:63], v[12:15], v[0:3], 0
	v_mov_b32_e32 v16, 0
	v_mov_b32_e32 v17, 0
	v_mfma_f32_16x16x32_bf16 v[56:59], v[12:15], v[8:11], 0
	v_mfma_f32_16x16x32_bf16 v[52:55], v[12:15], v[4:7], 0
	v_mfma_f32_16x16x32_bf16 v[48:51], v[12:15], v[64:67], 0
	v_mov_b32_e32 v12, 0
	v_mov_b32_e32 v14, 0
	v_mov_b32_e32 v15, 0
	s_and_saveexec_b64 s[2:3], s[40:41]
	ds_read_b128 v[14:17], v152 offset:5376
	s_or_b64 exec, exec, s[2:3]
	s_waitcnt lgkmcnt(0)
	v_mfma_f32_16x16x32_bf16 v[44:47], v[14:17], v[0:3], 0
	v_mov_b32_e32 v13, 0
	v_mfma_f32_16x16x32_bf16 v[40:43], v[14:17], v[8:11], 0
	v_mfma_f32_16x16x32_bf16 v[36:39], v[14:17], v[4:7], 0
	v_mfma_f32_16x16x32_bf16 v[32:35], v[14:17], v[64:67], 0
	v_mov_b32_e32 v14, 0
	v_mov_b32_e32 v15, 0
	s_and_saveexec_b64 s[2:3], s[40:41]
	ds_read_b128 v[12:15], v152 offset:6144
	s_or_b64 exec, exec, s[2:3]
	s_waitcnt lgkmcnt(0)
	v_mfma_f32_16x16x32_bf16 v[28:31], v[12:15], v[0:3], 0
	v_mov_b32_e32 v80, 0
	v_mov_b32_e32 v68, 0
	v_mov_b32_e32 v69, 0
	v_mfma_f32_16x16x32_bf16 v[24:27], v[12:15], v[8:11], 0
	v_mov_b32_e32 v70, 0
	v_mov_b32_e32 v71, 0
	v_mfma_f32_16x16x32_bf16 v[20:23], v[12:15], v[4:7], 0
	v_mfma_f32_16x16x32_bf16 v[16:19], v[12:15], v[64:67], 0
	s_and_saveexec_b64 s[2:3], s[40:41]
	ds_read_b128 v[68:71], v152 offset:6912
	s_or_b64 exec, exec, s[2:3]
	s_waitcnt lgkmcnt(0)
	v_mfma_f32_16x16x32_bf16 v[12:15], v[68:71], v[0:3], 0
	v_mfma_f32_16x16x32_bf16 v[8:11], v[68:71], v[8:11], 0
	v_mfma_f32_16x16x32_bf16 v[4:7], v[68:71], v[4:7], 0
	v_mfma_f32_16x16x32_bf16 v[0:3], v[68:71], v[64:67], 0
	v_mov_b32_e32 v144, v140
	s_or_b64 s[2:3], s[24:25], s[12:13]
	v_ashrrev_i32_e32 v82, 3, v144
	v_ashrrev_i32_e32 v83, 31, v82
	v_lshl_add_u64 v[64:65], s[2:3], 0, v[82:83]
	v_mov_b64_e32 v[66:67], s[60:61]
	v_mad_u64_u32 v[66:67], s[2:3], v64, s93, v[66:67]
	v_mov_b32_e32 v64, v67
	v_mad_u64_u32 v[64:65], s[2:3], v65, s93, v[64:65]
	v_mov_b32_e32 v67, v64
	v_lshl_add_u64 v[64:65], v[66:67], 0, s[62:63]
	v_lshlrev_b32_e32 v66, 4, v144
	v_and_b32_e32 v84, 0x70, v66
	v_mov_b32_e32 v85, v221
	v_lshl_add_u64 v[72:73], v[64:65], 0, v[84:85]
	v_add_co_u32_e32 v76, vcc, s55, v72
	v_addc_co_u32_e32 v77, vcc, 0, v73, vcc
	s_movk_i32 s2, 0x90
	v_mul_lo_u32 v81, v82, s2
	v_add3_u32 v81, s9, v84, v81
	s_waitcnt lgkmcnt(0)
	s_cmpk_lg_i32 s92, 0x100
	s_cbranch_scc1 .Lmy_hq_nopf
	s_bitcmp1_b32 s30, 4
	s_cbranch_scc1 .Lmy_hq_nopf
	s_add_i32 s98, s30, 16
	s_and_b32 s99, s98, 31
	s_xor_b32 vcc_lo, s99, 63
	s_cmp_lg_u64 s[10:11], 0
	s_cselect_b32 s99, s99, vcc_lo
	s_lshl_b32 s99, s99, 7
	s_ashr_i32 vcc_lo, s98, 7
	s_lshl_b32 vcc_lo, vcc_lo, 13
	s_or_b32 s99, s99, vcc_lo
	s_ashr_i32 s98, s98, 5
	s_lshl_b32 s98, s98, 6
	s_and_b32 s98, s98, 0xc0
	s_lshl_b32 s98, s98, 1
	v_or_b32_e32 v158, s99, v142
	v_mov_b64_e32 v[154:155], s[60:61]
	s_nop 0
	v_mad_u64_u32 v[154:155], vcc, v158, s93, v[154:155]
	s_nop 1
	v_add_co_u32_e32 v154, vcc, s98, v154
	s_nop 1
	v_addc_co_u32_e32 v155, vcc, 0, v155, vcc
	v_lshl_add_u64 v[154:155], v[154:155], 0, v[220:221]
	v_add_co_u32_e32 v156, vcc, s55, v154
	s_nop 1
	v_addc_co_u32_e32 v157, vcc, 0, v155, vcc
	global_load_dwordx4 v[200:203], v[154:155], off offset:512
	global_load_dwordx4 v[204:207], v[154:155], off offset:1024
	global_load_dwordx4 v[208:211], v[156:157], off offset:512
	global_load_dwordx4 v[212:215], v[156:157], off offset:1024
	v_ashrrev_i32_e32 v158, 3, v140
	v_mov_b32_e32 v159, s99
	v_or_b32_e32 v159, s12, v159
	v_add_u32_e32 v158, v159, v158
	v_mul_lo_u32 v158, v158, s93
	v_and_b32_e32 v159, 7, v140
	v_lshlrev_b32_e32 v159, 4, v159
	v_add3_u32 v158, v158, v159, s98
	global_load_dwordx4 v[216:219], v158, s[60:61] offset:512
	global_load_dwordx4 v[222:225], v158, s[60:61] offset:1024
	v_add_u32_e32 v159, s55, v158
	global_load_dwordx4 v[226:229], v159, s[60:61] offset:512
	global_load_dwordx4 v[230:233], v159, s[60:61] offset:1024
	s_and_b64 vcc, exec, s[0:1]
	s_waitcnt vmcnt(8)
	s_branch .Lmy_hq_pfj
.Lmy_hq_nopf:
	s_and_b64 vcc, exec, s[0:1]
	s_waitcnt vmcnt(0)
.Lmy_hq_pfj:
	ds_write_b128 v81, v[160:163]
	ds_write_b128 v81, v[164:167] offset:2304
	ds_write_b128 v81, v[168:171] offset:1152
	ds_write_b128 v81, v[172:175] offset:3456
	s_waitcnt lgkmcnt(0)
	s_cbranch_vccnz .LBB0_480
	v_mov_b32_e32 v80, v177
